# scan: waves 4-7 do COMMIT arithmetic in the shadow of stage-Y operand reads and ISSUE (chunk c+4) at the end of stage Y; merged X+S stage now only MFMA+solve on waves 4-7 and PREP on waves 0-3
# speedup vs baseline: 1.0120x; 1.0078x over previous
.Lpq0_end:
	s_waitcnt lgkmcnt(0)
	s_barrier
	v_add_u32_e32 v200, v146, v145
	v_add_u32_e32 v112, v156, v163
	ds_read_b128 v[48:51], v180
	ds_read_b128 v[52:55], v112 offset:62976
	ds_read_b128 v[56:59], v112 offset:64256
	v_sub_u32_e32 v113, v164, v143
	v_mad_u32_u24 v113, v145, 5, v113
	v_add_u32_e32 v113, 0x18d00, v113
	ds_read_b128 v[88:91], v113
	ds_read_b128 v[92:95], v113 offset:64
	s_and_b64 s[98:99], s[56:57], exec
	s_cbranch_scc0 .Lcp0
	s_cmp_gt_u32 s36, 62
	s_cbranch_scc1 .Lcp0
	s_waitcnt vmcnt(1)
	v_lshlrev_b32_e32 v136, 16, v1
	v_and_b32_e32 v137, 0xffff0000, v1
	v_pk_mul_f32 v[124:125], v[102:103], v[136:137]
	v_lshlrev_b32_e32 v126, 16, v3
	v_pk_mul_f32 v[124:125], v[108:109], v[124:125] op_sel_hi:[0,1]
	v_and_b32_e32 v127, 0xffff0000, v3
	v_lshlrev_b32_e32 v130, 16, v4
	v_and_b32_e32 v131, 0xffff0000, v4
	v_pk_add_f32 v[128:129], v[130:131], -1.0 op_sel_hi:[1,0]
	v_pk_mul_f32 v[130:131], v[130:131], v[124:125] neg_lo:[0,1] neg_hi:[0,1]
	v_pk_fma_f32 v[128:129], v[104:105], v[128:129], 1.0 op_sel_hi:[1,1,0]
	s_nop 0
	v_pk_mul_f32 v[128:129], v[128:129], v[136:137]
	v_lshlrev_b32_e32 v132, 16, v0
	v_and_b32_e32 v133, 0xffff0000, v0
	v_lshlrev_b32_e32 v134, 16, v2
	v_and_b32_e32 v135, 0xffff0000, v2
	v_lshlrev_b32_e32 v136, 16, v202
	v_and_b32_e32 v137, 0xffff0000, v202
	v_pk_mul_f32 v[214:215], v[102:103], v[136:137]
	v_lshlrev_b32_e32 v216, 16, v204
	v_pk_mul_f32 v[214:215], v[206:207], v[214:215] op_sel_hi:[0,1]
	v_and_b32_e32 v217, 0xffff0000, v204
	v_lshlrev_b32_e32 v228, 16, v205
	v_and_b32_e32 v229, 0xffff0000, v205
	v_pk_add_f32 v[218:219], v[228:229], -1.0 op_sel_hi:[1,0]
	v_pk_mul_f32 v[228:229], v[228:229], v[214:215] neg_lo:[0,1] neg_hi:[0,1]
	v_pk_fma_f32 v[218:219], v[104:105], v[218:219], 1.0 op_sel_hi:[1,1,0]
	s_nop 0
	v_pk_mul_f32 v[218:219], v[218:219], v[136:137]
	v_lshlrev_b32_e32 v230, 16, v201
	v_and_b32_e32 v231, 0xffff0000, v201
	v_lshlrev_b32_e32 v232, 16, v203
	v_and_b32_e32 v233, 0xffff0000, v203
.Lcp0:
	v_mul_u32_u24_e32 v114, 5, v145
	v_sub_u32_e32 v114, v143, v114
	v_mul_i32_i24_e32 v114, 0x47, v114
	v_ashrrev_i32_e32 v114, 1, v114
	v_add_u32_e32 v114, v181, v114
	s_waitcnt lgkmcnt(2)
	v_mfma_f32_16x16x32_bf16 v[14:17], v[52:55], v[48:51], v[14:17]
	v_mfma_f32_16x16x32_bf16 v[18:21], v[56:59], v[48:51], v[18:21]
	s_waitcnt lgkmcnt(0)
	s_and_saveexec_b64 s[2:3], s[56:57]
	s_cbranch_execz .Lsy0_r1
	ds_read_b128 v[62:65], v175
	ds_read_b128 v[66:69], v200

.LBB0_422:
	s_or_b64 exec, exec, s[2:3]
	s_cmp_lt_u32 s36, 63
	s_cselect_b64 vcc, -1, 0
	s_cmp_gt_u32 s36, 62
	s_cbranch_scc1 .LBB0_424
	s_and_b64 s[98:99], s[56:57], exec
	s_cbranch_scc0 .LBB0_424
	ds_write2_b64 v106, v[124:125], v[126:127] offset1:32
	ds_write2_b64 v106, v[128:129], v[130:131] offset0:64 offset1:96
	ds_write2_b64 v106, v[132:133], v[134:135] offset0:128 offset1:160
	s_and_b64 s[98:99], s[12:13], exec
	s_movk_i32 s98, 0x3000
	s_cselect_b32 s98, 0xffffd000, s98
	v_add_u32_e32 v136, s98, v106
	ds_write2_b64 v136, v[214:215], v[216:217] offset1:32
	ds_write2_b64 v136, v[218:219], v[228:229] offset0:64 offset1:96
	ds_write2_b64 v136, v[230:231], v[232:233] offset0:128 offset1:160
	s_cmp_gt_u32 s36, 61
	s_cbranch_scc1 .LBB0_424
	s_add_i32 s24, s19, 0xffffffb0
	s_add_i32 s25, s21, 64
	s_and_b64 s[98:99], s[12:13], exec
	s_cselect_b32 s24, s25, s24
	v_lshl_add_u32 v194, s24, 6, v183
	v_lshlrev_b32_e32 v112, 1, v194
	global_load_dword v0, v112, s[44:45]
	global_load_dword v201, v112, s[44:45] offset:-1024
	global_load_dword v1, v112, s[42:43]
	global_load_dword v202, v112, s[42:43] offset:-1024
	global_load_dword v2, v112, s[0:1]
	global_load_dword v203, v112, s[0:1] offset:-1024
	global_load_dword v3, v112, s[34:35]
	global_load_dword v204, v112, s[34:35] offset:-1024
	global_load_dword v4, v112, s[76:77]
	global_load_dword v205, v112, s[76:77] offset:-1024
	v_add_u32_e32 v194, s24, v184
	v_lshlrev_b32_e32 v114, 2, v194
	global_load_dword v108, v114, s[40:41]
	global_load_dword v206, v114, s[40:41] offset:-32

.Lpq1_end:
	s_waitcnt lgkmcnt(0)
	s_barrier
	s_and_b64 s[24:25], s[46:47], s[2:3]
	ds_read_b128 v[48:51], v180 offset:5120
	ds_read_b128 v[52:55], v170 offset:5120
	ds_read_b128 v[56:59], v170 offset:6400
	v_sub_u32_e32 v113, v164, v143
	v_mad_u32_u24 v113, v145, 5, v113
	v_add_u32_e32 v113, 0x18e00, v113
	ds_read_b128 v[88:91], v113
	ds_read_b128 v[92:95], v113 offset:64
	s_and_b64 s[98:99], s[56:57], exec
	s_cbranch_scc0 .Lcp1
	s_cmp_gt_u32 s36, 62
	s_cbranch_scc1 .Lcp1
	s_waitcnt vmcnt(1)
	v_lshlrev_b32_e32 v136, 16, v6
	v_and_b32_e32 v137, 0xffff0000, v6
	v_pk_mul_f32 v[124:125], v[102:103], v[136:137]
	v_lshlrev_b32_e32 v126, 16, v8
	v_pk_mul_f32 v[124:125], v[110:111], v[124:125] op_sel_hi:[0,1]
	v_and_b32_e32 v127, 0xffff0000, v8
	v_lshlrev_b32_e32 v130, 16, v9
	v_and_b32_e32 v131, 0xffff0000, v9
	v_pk_add_f32 v[128:129], v[130:131], -1.0 op_sel_hi:[1,0]
	v_pk_mul_f32 v[130:131], v[130:131], v[124:125] neg_lo:[0,1] neg_hi:[0,1]
	v_pk_fma_f32 v[128:129], v[104:105], v[128:129], 1.0 op_sel_hi:[1,1,0]
	s_nop 0
	v_pk_mul_f32 v[128:129], v[128:129], v[136:137]
	v_lshlrev_b32_e32 v132, 16, v5
	v_and_b32_e32 v133, 0xffff0000, v5
	v_lshlrev_b32_e32 v134, 16, v7
	v_and_b32_e32 v135, 0xffff0000, v7
	v_lshlrev_b32_e32 v136, 16, v208
	v_and_b32_e32 v137, 0xffff0000, v208
	v_pk_mul_f32 v[214:215], v[102:103], v[136:137]
	v_lshlrev_b32_e32 v216, 16, v210
	v_pk_mul_f32 v[214:215], v[212:213], v[214:215] op_sel_hi:[0,1]
	v_and_b32_e32 v217, 0xffff0000, v210
	v_lshlrev_b32_e32 v228, 16, v211
	v_and_b32_e32 v229, 0xffff0000, v211
	v_pk_add_f32 v[218:219], v[228:229], -1.0 op_sel_hi:[1,0]
	v_pk_mul_f32 v[228:229], v[228:229], v[214:215] neg_lo:[0,1] neg_hi:[0,1]
	v_pk_fma_f32 v[218:219], v[104:105], v[218:219], 1.0 op_sel_hi:[1,1,0]
	s_nop 0
	v_pk_mul_f32 v[218:219], v[218:219], v[136:137]
	v_lshlrev_b32_e32 v230, 16, v207
	v_and_b32_e32 v231, 0xffff0000, v207
	v_lshlrev_b32_e32 v232, 16, v209
	v_and_b32_e32 v233, 0xffff0000, v209
.Lcp1:
	v_mul_u32_u24_e32 v114, 5, v145
	v_sub_u32_e32 v114, v143, v114
	v_mul_i32_i24_e32 v114, 0x47, v114
	v_ashrrev_i32_e32 v114, 1, v114
	v_add_u32_e32 v114, v181, v114
	s_waitcnt lgkmcnt(2)
	v_mfma_f32_16x16x32_bf16 v[14:17], v[52:55], v[48:51], v[14:17]
	v_mfma_f32_16x16x32_bf16 v[18:21], v[56:59], v[48:51], v[18:21]
	s_waitcnt lgkmcnt(0)
	s_and_saveexec_b64 s[74:75], s[56:57]
	s_cbranch_execz .Lsy1_r1
	ds_read_b128 v[62:65], v175 offset:5120
	ds_read_b128 v[66:69], v200 offset:1280

.LBB0_451:
	s_or_b64 exec, exec, s[2:3]
	s_andn2_b64 vcc, exec, vcc
	s_cbranch_vccnz .LBB0_453
	s_and_b64 s[98:99], s[56:57], exec
	s_cbranch_scc0 .LBB0_453
	ds_write2_b64 v107, v[124:125], v[126:127] offset1:32
	ds_write2_b64 v107, v[128:129], v[130:131] offset0:64 offset1:96
	ds_write2_b64 v107, v[132:133], v[134:135] offset0:128 offset1:160
	s_and_b64 s[98:99], s[12:13], exec
	s_movk_i32 s98, 0x3000
	s_cselect_b32 s98, 0xffffd000, s98
	v_add_u32_e32 v136, s98, v107
	ds_write2_b64 v136, v[214:215], v[216:217] offset1:32
	ds_write2_b64 v136, v[218:219], v[228:229] offset0:64 offset1:96
	ds_write2_b64 v136, v[230:231], v[232:233] offset0:128 offset1:160
	s_cmp_gt_u32 s36, 61
	s_cbranch_scc1 .LBB0_453
	s_add_i32 s24, s19, 0xffffffa0
	s_add_i32 s25, s21, 0x50
	s_and_b64 s[98:99], s[12:13], exec
	s_cselect_b32 s24, s25, s24
	v_lshl_add_u32 v194, s24, 6, v183
	v_lshlrev_b32_e32 v112, 1, v194
	global_load_dword v5, v112, s[44:45]
	global_load_dword v207, v112, s[44:45] offset:-1024
	global_load_dword v6, v112, s[42:43]
	global_load_dword v208, v112, s[42:43] offset:-1024
	global_load_dword v7, v112, s[0:1]
	global_load_dword v209, v112, s[0:1] offset:-1024
	global_load_dword v8, v112, s[34:35]
	global_load_dword v210, v112, s[34:35] offset:-1024
	global_load_dword v9, v112, s[76:77]
	global_load_dword v211, v112, s[76:77] offset:-1024
	v_add_u32_e32 v194, s24, v184
	v_lshlrev_b32_e32 v114, 2, v194
	global_load_dword v110, v114, s[40:41]
	global_load_dword v212, v114, s[40:41] offset:-32
